# v79 + P0 plain-conversion wave pieces dealt 4 per wave to blocks with two ada-projection jobs and 6 per wave to the others
# baseline (speedup 1.0000x reference)
.Lwf_loop:
	s_lshl_b32 s7, s6, 11
	s_lshl_b32 s8, s6, 10
	s_addk_i32 s8, 0xc00
	s_cmp_ge_u32 s6, 4
	s_cselect_b32 s7, s8, s7
	s_add_i32 s7, s7, s58
	s_and_b32 s8, s7, 1
	s_lshr_b32 s7, s7, 1
	s_addk_i32 s7, 0x100
	s_mov_b32 s30, 2
	s_cmpk_ge_i32 s7, 0x300
	s_cselect_b32 s30, 3, s30
	s_cmpk_ge_i32 s7, 0x500
	s_cselect_b32 s30, 4, s30
	s_cmpk_ge_i32 s7, 0x700
	s_cselect_b32 s30, 5, s30
	s_cmpk_ge_i32 s7, 0x900
	s_cselect_b32 s30, 6, s30
	s_cmpk_ge_i32 s7, 0xb00
	s_cselect_b32 s30, 7, s30
	s_cmpk_ge_i32 s7, 0xd00
	s_cselect_b32 s30, 8, s30
	s_cmpk_ge_i32 s7, 0xf00
	s_cselect_b32 s30, 9, s30
	s_cmpk_ge_i32 s7, 0x1100
	s_cselect_b32 s30, 10, s30
	s_cmpk_ge_i32 s7, 0x1280
	s_cselect_b32 s30, 11, s30
	s_cmpk_ge_i32 s7, 0x1400
	s_cselect_b32 s30, 12, s30
	s_cmpk_ge_i32 s7, 0x1480
	s_cselect_b32 s30, 13, s30
	s_mul_i32 s59, s30, 48
	s_add_u32 s10, s0, s59
	s_addc_u32 s11, s1, 0
	s_load_dwordx2 s[50:51], s[10:11], 0x100
	s_load_dwordx2 s[52:53], s[10:11], 0x110
	s_load_dwordx2 s[90:91], s[10:11], 0x118
	s_load_dword s30, s[10:11], 0x128
	s_load_dwordx2 vcc, s[0:1], 0xf8
	s_waitcnt lgkmcnt(0)
	s_sub_i32 s7, s7, s30
	s_lshr_b32 s59, s90, 7
	s_add_i32 s10, s59, -1
	s_and_b32 s10, s7, s10
	s_ff1_i32_b32 s59, s59
	s_lshr_b32 s7, s7, s59
	s_lshl_b32 s10, s10, 7
	s_lshl_b32 s8, s8, 6
	s_add_i32 s10, s10, s8
	s_lshl_b32 s11, s7, 6
	s_mul_i32 s59, s10, s91
	s_add_i32 s59, s59, s11
	s_lshl_b32 s59, s59, 2
	s_add_u32 s50, s50, s59
	s_addc_u32 s51, s51, 0
	s_mul_i32 s59, s11, s90
	s_add_i32 s59, s59, s10
	s_lshl_b32 s59, s59, 1
	s_add_u32 s52, s52, s59
	s_addc_u32 s53, s53, 0
	s_add_u32 s52, s52, vcc_lo
	s_addc_u32 s53, s53, vcc_hi
	s_lshl_b32 s54, s90, 1
	v_mul_lo_u32 v85, v28, s54
	v_lshl_add_u32 v85, v29, 4, v85
	s_lshl_b32 s54, s54, 3
	s_mov_b32 s55, 0
	s_lshl_b32 s91, s91, 2
	global_load_dword v0, v26, s[50:51] nt
	s_add_u32 s50, s50, s91
	s_addc_u32 s51, s51, 0
	global_load_dword v1, v26, s[50:51] nt
	s_add_u32 s50, s50, s91
	s_addc_u32 s51, s51, 0
	global_load_dword v2, v26, s[50:51] nt
	s_add_u32 s50, s50, s91
	s_addc_u32 s51, s51, 0
	global_load_dword v3, v26, s[50:51] nt
	s_add_u32 s50, s50, s91
	s_addc_u32 s51, s51, 0
	global_load_dword v4, v26, s[50:51] nt
	s_add_u32 s50, s50, s91
	s_addc_u32 s51, s51, 0
	global_load_dword v5, v26, s[50:51] nt
	s_add_u32 s50, s50, s91
	s_addc_u32 s51, s51, 0
	global_load_dword v6, v26, s[50:51] nt
	s_add_u32 s50, s50, s91
	s_addc_u32 s51, s51, 0
	global_load_dword v7, v26, s[50:51] nt
	s_add_u32 s50, s50, s91
	s_addc_u32 s51, s51, 0
	global_load_dword v8, v26, s[50:51] nt
	s_add_u32 s50, s50, s91
	s_addc_u32 s51, s51, 0
	global_load_dword v9, v26, s[50:51] nt
	s_add_u32 s50, s50, s91
	s_addc_u32 s51, s51, 0
	global_load_dword v10, v26, s[50:51] nt
	s_add_u32 s50, s50, s91
	s_addc_u32 s51, s51, 0
	global_load_dword v11, v26, s[50:51] nt
	s_add_u32 s50, s50, s91
	s_addc_u32 s51, s51, 0
	global_load_dword v12, v26, s[50:51] nt
	s_add_u32 s50, s50, s91
	s_addc_u32 s51, s51, 0
	global_load_dword v13, v26, s[50:51] nt
	s_add_u32 s50, s50, s91
	s_addc_u32 s51, s51, 0
	global_load_dword v14, v26, s[50:51] nt
	s_add_u32 s50, s50, s91
	s_addc_u32 s51, s51, 0
	global_load_dword v15, v26, s[50:51] nt
	s_add_u32 s50, s50, s91
	s_addc_u32 s51, s51, 0
	global_load_dword v30, v26, s[50:51] nt
	s_add_u32 s50, s50, s91
	s_addc_u32 s51, s51, 0
	global_load_dword v31, v26, s[50:51] nt
	s_add_u32 s50, s50, s91
	s_addc_u32 s51, s51, 0
	global_load_dword v32, v26, s[50:51] nt
	s_add_u32 s50, s50, s91
	s_addc_u32 s51, s51, 0
	global_load_dword v33, v26, s[50:51] nt
	s_add_u32 s50, s50, s91
	s_addc_u32 s51, s51, 0
	global_load_dword v34, v26, s[50:51] nt
	s_add_u32 s50, s50, s91
	s_addc_u32 s51, s51, 0
	global_load_dword v35, v26, s[50:51] nt
	s_add_u32 s50, s50, s91
	s_addc_u32 s51, s51, 0
	global_load_dword v36, v26, s[50:51] nt
	s_add_u32 s50, s50, s91
	s_addc_u32 s51, s51, 0
	global_load_dword v37, v26, s[50:51] nt
	s_add_u32 s50, s50, s91
	s_addc_u32 s51, s51, 0
	global_load_dword v38, v26, s[50:51] nt
	s_add_u32 s50, s50, s91
	s_addc_u32 s51, s51, 0
	global_load_dword v39, v26, s[50:51] nt
	s_add_u32 s50, s50, s91
	s_addc_u32 s51, s51, 0
	global_load_dword v40, v26, s[50:51] nt
	s_add_u32 s50, s50, s91
	s_addc_u32 s51, s51, 0
	global_load_dword v41, v26, s[50:51] nt
	s_add_u32 s50, s50, s91
	s_addc_u32 s51, s51, 0
	global_load_dword v42, v26, s[50:51] nt
	s_add_u32 s50, s50, s91
	s_addc_u32 s51, s51, 0
	global_load_dword v43, v26, s[50:51] nt
	s_add_u32 s50, s50, s91
	s_addc_u32 s51, s51, 0
	global_load_dword v44, v26, s[50:51] nt
	s_add_u32 s50, s50, s91
	s_addc_u32 s51, s51, 0
	global_load_dword v45, v26, s[50:51] nt
	s_add_u32 s50, s50, s91
	s_addc_u32 s51, s51, 0
	global_load_dword v46, v26, s[50:51] nt
	s_add_u32 s50, s50, s91
	s_addc_u32 s51, s51, 0
	global_load_dword v47, v26, s[50:51] nt
	s_add_u32 s50, s50, s91
	s_addc_u32 s51, s51, 0
	global_load_dword v48, v26, s[50:51] nt
	s_add_u32 s50, s50, s91
	s_addc_u32 s51, s51, 0
	global_load_dword v49, v26, s[50:51] nt
	s_add_u32 s50, s50, s91
	s_addc_u32 s51, s51, 0
	global_load_dword v50, v26, s[50:51] nt
	s_add_u32 s50, s50, s91
	s_addc_u32 s51, s51, 0
	global_load_dword v51, v26, s[50:51] nt
	s_add_u32 s50, s50, s91
	s_addc_u32 s51, s51, 0
	global_load_dword v52, v26, s[50:51] nt
	s_add_u32 s50, s50, s91
	s_addc_u32 s51, s51, 0
	global_load_dword v53, v26, s[50:51] nt
	s_add_u32 s50, s50, s91
	s_addc_u32 s51, s51, 0
	global_load_dword v54, v26, s[50:51] nt
	s_add_u32 s50, s50, s91
	s_addc_u32 s51, s51, 0
	global_load_dword v55, v26, s[50:51] nt
	s_add_u32 s50, s50, s91
	s_addc_u32 s51, s51, 0
	global_load_dword v56, v26, s[50:51] nt
	s_add_u32 s50, s50, s91
	s_addc_u32 s51, s51, 0
	global_load_dword v57, v26, s[50:51] nt
	s_add_u32 s50, s50, s91
	s_addc_u32 s51, s51, 0
	global_load_dword v58, v26, s[50:51] nt
	s_add_u32 s50, s50, s91
	s_addc_u32 s51, s51, 0
	global_load_dword v59, v26, s[50:51] nt
	s_add_u32 s50, s50, s91
	s_addc_u32 s51, s51, 0
	global_load_dword v60, v26, s[50:51] nt
	s_add_u32 s50, s50, s91
	s_addc_u32 s51, s51, 0
	global_load_dword v61, v26, s[50:51] nt
	s_add_u32 s50, s50, s91
	s_addc_u32 s51, s51, 0
	global_load_dword v62, v26, s[50:51] nt
	s_add_u32 s50, s50, s91
	s_addc_u32 s51, s51, 0
	global_load_dword v63, v26, s[50:51] nt
	s_add_u32 s50, s50, s91
	s_addc_u32 s51, s51, 0
	global_load_dword v64, v26, s[50:51] nt
	s_add_u32 s50, s50, s91
	s_addc_u32 s51, s51, 0
	global_load_dword v65, v26, s[50:51] nt
	s_add_u32 s50, s50, s91
	s_addc_u32 s51, s51, 0
	global_load_dword v66, v26, s[50:51] nt
	s_add_u32 s50, s50, s91
	s_addc_u32 s51, s51, 0
	global_load_dword v67, v26, s[50:51] nt
	s_add_u32 s50, s50, s91
	s_addc_u32 s51, s51, 0
	global_load_dword v68, v26, s[50:51] nt
	s_add_u32 s50, s50, s91
	s_addc_u32 s51, s51, 0
	global_load_dword v69, v26, s[50:51] nt
	s_add_u32 s50, s50, s91
	s_addc_u32 s51, s51, 0
	global_load_dword v70, v26, s[50:51] nt
	s_add_u32 s50, s50, s91
	s_addc_u32 s51, s51, 0
	global_load_dword v71, v26, s[50:51] nt
	s_add_u32 s50, s50, s91
	s_addc_u32 s51, s51, 0
	global_load_dword v72, v26, s[50:51] nt
	s_add_u32 s50, s50, s91
	s_addc_u32 s51, s51, 0
	global_load_dword v73, v26, s[50:51] nt
	s_add_u32 s50, s50, s91
	s_addc_u32 s51, s51, 0
	global_load_dword v74, v26, s[50:51] nt
	s_add_u32 s50, s50, s91
	s_addc_u32 s51, s51, 0
	global_load_dword v75, v26, s[50:51] nt
	s_add_u32 s50, s50, s91
	s_addc_u32 s51, s51, 0
	global_load_dword v76, v26, s[50:51] nt
	s_add_u32 s50, s50, s91
	s_addc_u32 s51, s51, 0
	global_load_dword v77, v26, s[50:51] nt
	s_waitcnt vmcnt(48)
	v_cvt_pk_bf16_f32 v78, v0, v1
	ds_write_b32 v27, v78 offset:0
	v_cvt_pk_bf16_f32 v79, v2, v3
	ds_write_b32 v27, v79 offset:4
	v_cvt_pk_bf16_f32 v80, v4, v5
	ds_write_b32 v27, v80 offset:8
	v_cvt_pk_bf16_f32 v81, v6, v7
	ds_write_b32 v27, v81 offset:12
	v_cvt_pk_bf16_f32 v82, v8, v9
	ds_write_b32 v27, v82 offset:16
	v_cvt_pk_bf16_f32 v83, v10, v11
	ds_write_b32 v27, v83 offset:20
	v_cvt_pk_bf16_f32 v78, v12, v13
	ds_write_b32 v27, v78 offset:24
	v_cvt_pk_bf16_f32 v79, v14, v15
	ds_write_b32 v27, v79 offset:28
	s_waitcnt vmcnt(32)
	v_cvt_pk_bf16_f32 v78, v30, v31
	ds_write_b32 v27, v78 offset:32
	v_cvt_pk_bf16_f32 v79, v32, v33
	ds_write_b32 v27, v79 offset:36
	v_cvt_pk_bf16_f32 v80, v34, v35
	ds_write_b32 v27, v80 offset:40
	v_cvt_pk_bf16_f32 v81, v36, v37
	ds_write_b32 v27, v81 offset:44
	v_cvt_pk_bf16_f32 v82, v38, v39
	ds_write_b32 v27, v82 offset:48
	v_cvt_pk_bf16_f32 v83, v40, v41
	ds_write_b32 v27, v83 offset:52
	v_cvt_pk_bf16_f32 v78, v42, v43
	ds_write_b32 v27, v78 offset:56
	v_cvt_pk_bf16_f32 v79, v44, v45
	ds_write_b32 v27, v79 offset:60
	s_waitcnt vmcnt(16)
	v_cvt_pk_bf16_f32 v78, v46, v47
	ds_write_b32 v27, v78 offset:64
	v_cvt_pk_bf16_f32 v79, v48, v49
	ds_write_b32 v27, v79 offset:68
	v_cvt_pk_bf16_f32 v80, v50, v51
	ds_write_b32 v27, v80 offset:72
	v_cvt_pk_bf16_f32 v81, v52, v53
	ds_write_b32 v27, v81 offset:76
	v_cvt_pk_bf16_f32 v82, v54, v55
	ds_write_b32 v27, v82 offset:80
	v_cvt_pk_bf16_f32 v83, v56, v57
	ds_write_b32 v27, v83 offset:84
	v_cvt_pk_bf16_f32 v78, v58, v59
	ds_write_b32 v27, v78 offset:88
	v_cvt_pk_bf16_f32 v79, v60, v61
	ds_write_b32 v27, v79 offset:92
	s_waitcnt vmcnt(0)
	v_cvt_pk_bf16_f32 v78, v62, v63
	ds_write_b32 v27, v78 offset:96
	v_cvt_pk_bf16_f32 v79, v64, v65
	ds_write_b32 v27, v79 offset:100
	v_cvt_pk_bf16_f32 v80, v66, v67
	ds_write_b32 v27, v80 offset:104
	v_cvt_pk_bf16_f32 v81, v68, v69
	ds_write_b32 v27, v81 offset:108
	v_cvt_pk_bf16_f32 v82, v70, v71
	ds_write_b32 v27, v82 offset:112
	v_cvt_pk_bf16_f32 v83, v72, v73
	ds_write_b32 v27, v83 offset:116
	v_cvt_pk_bf16_f32 v78, v74, v75
	ds_write_b32 v27, v78 offset:120
	v_cvt_pk_bf16_f32 v79, v76, v77
	ds_write_b32 v27, v79 offset:124
	s_waitcnt lgkmcnt(0)
	ds_read_b128 v[86:89], v24 offset:0
	ds_read_b128 v[90:93], v24 offset:1152
	ds_read_b128 v[94:97], v24 offset:2304
	ds_read_b128 v[98:101], v24 offset:3456
	s_waitcnt lgkmcnt(3)
	global_store_dwordx4 v85, v[86:89], s[52:53]
	s_add_u32 s52, s52, s54
	s_addc_u32 s53, s53, s55
	s_waitcnt lgkmcnt(2)
	global_store_dwordx4 v85, v[90:93], s[52:53]
	s_add_u32 s52, s52, s54
	s_addc_u32 s53, s53, s55
	s_waitcnt lgkmcnt(1)
	global_store_dwordx4 v85, v[94:97], s[52:53]
	s_add_u32 s52, s52, s54
	s_addc_u32 s53, s53, s55
	s_waitcnt lgkmcnt(0)
	global_store_dwordx4 v85, v[98:101], s[52:53]
	s_add_u32 s52, s52, s54
	s_addc_u32 s53, s53, s55
	s_nop 4
	ds_read_b128 v[86:89], v24 offset:4608
	ds_read_b128 v[90:93], v24 offset:5760
	ds_read_b128 v[94:97], v24 offset:6912
	ds_read_b128 v[98:101], v24 offset:8064
	s_waitcnt lgkmcnt(3)
	global_store_dwordx4 v85, v[86:89], s[52:53]
	s_add_u32 s52, s52, s54
	s_addc_u32 s53, s53, s55
	s_waitcnt lgkmcnt(2)
	global_store_dwordx4 v85, v[90:93], s[52:53]
	s_add_u32 s52, s52, s54
	s_addc_u32 s53, s53, s55
	s_waitcnt lgkmcnt(1)
	global_store_dwordx4 v85, v[94:97], s[52:53]
	s_add_u32 s52, s52, s54
	s_addc_u32 s53, s53, s55
	s_waitcnt lgkmcnt(0)
	global_store_dwordx4 v85, v[98:101], s[52:53]
	s_add_u32 s52, s52, s54
	s_addc_u32 s53, s53, s55
	s_add_i32 s6, s6, 1
	s_cmp_ge_u32 s92, 0x80
	s_cselect_b32 s7, 6, 4
	s_cmp_lt_u32 s6, s7
	s_cbranch_scc1 .Lwf_loop
	s_cmp_ge_u32 s92, 0x80
	s_movk_i32 s7, 0x1700
	s_cselect_b32 s89, 0x1600, s7
	s_add_i32 s89, s89, s92
	s_cmp_ge_i32 s89, s62
	s_cbranch_scc1 .LBB0_113
